# attention pass finalize: norm-weight loads hoisted before the barrier, permlane32 swaps instead of ds_bpermute, batched LDS partial-sum reads
# speedup vs baseline: 1.0037x; 1.0037x over previous
.LBB0_282:
	s_load_dwordx2 s[40:41], s[8:9], 0x68
	v_add_lshl_u32 v193, v164, v199, 2
	s_lshl_b32 s4, s21, 2
	v_mov_b32_e32 v32, v251
	s_nop 1
	v_permlane32_swap_b32_e32 v32, v251
	s_waitcnt lgkmcnt(0)
	s_add_u32 s40, s40, s4
	s_addc_u32 s41, s41, 0
	global_load_dwordx4 v[126:129], v193, s[40:41]
	global_load_dwordx4 v[96:99], v193, s[40:41] offset:32
	global_load_dwordx4 v[100:103], v193, s[40:41] offset:64
	global_load_dwordx4 v[104:107], v193, s[40:41] offset:96
	global_load_dwordx4 v[108:111], v193, s[40:41] offset:128
	global_load_dwordx4 v[114:117], v193, s[40:41] offset:160
	global_load_dwordx4 v[118:121], v193, s[40:41] offset:192
	global_load_dwordx4 v[122:125], v193, s[40:41] offset:224
	v_add_f32_e32 v32, v251, v32
	v_div_scale_f32 v33, s[0:1], v32, v32, 1.0
	v_rcp_f32_e32 v34, v33
	v_div_scale_f32 v35, vcc, 1.0, v32, 1.0
	v_fma_f32 v36, -v33, v34, 1.0
	v_fmac_f32_e32 v34, v36, v34
	v_mul_f32_e32 v36, v35, v34
	v_fma_f32 v37, -v33, v36, v35
	v_fmac_f32_e32 v36, v37, v34
	v_fma_f32 v33, -v33, v36, v35
	v_div_fmas_f32 v33, v33, v34, v36
	v_div_fixup_f32 v36, v33, v32, 1.0
	v_pk_mul_f32 v[34:35], v[16:17], v[36:37] op_sel_hi:[1,0]
	v_pk_mul_f32 v[32:33], v[18:19], v[36:37] op_sel_hi:[1,0]
	v_mul_f32_e32 v16, v35, v35
	v_fmac_f32_e32 v16, v34, v34
	v_fmac_f32_e32 v16, v32, v32
	v_pk_mul_f32 v[20:21], v[20:21], v[36:37] op_sel_hi:[1,0]
	v_fmac_f32_e32 v16, v33, v33
	v_fmac_f32_e32 v16, v20, v20
	v_pk_mul_f32 v[22:23], v[22:23], v[36:37] op_sel_hi:[1,0]
	v_fmac_f32_e32 v16, v21, v21
	v_fmac_f32_e32 v16, v22, v22
	v_pk_mul_f32 v[24:25], v[24:25], v[36:37] op_sel_hi:[1,0]
	v_fmac_f32_e32 v16, v23, v23
	v_fmac_f32_e32 v16, v24, v24
	v_pk_mul_f32 v[26:27], v[26:27], v[36:37] op_sel_hi:[1,0]
	v_fmac_f32_e32 v16, v25, v25
	v_fmac_f32_e32 v16, v26, v26
	v_pk_mul_f32 v[28:29], v[28:29], v[36:37] op_sel_hi:[1,0]
	v_fmac_f32_e32 v16, v27, v27
	v_fmac_f32_e32 v16, v28, v28
	v_pk_mul_f32 v[30:31], v[30:31], v[36:37] op_sel_hi:[1,0]
	v_fmac_f32_e32 v16, v29, v29
	v_fmac_f32_e32 v16, v30, v30
	v_fmac_f32_e32 v16, v31, v31
	v_pk_mul_f32 v[0:1], v[0:1], v[36:37] op_sel_hi:[1,0]
	v_pk_mul_f32 v[2:3], v[2:3], v[36:37] op_sel_hi:[1,0]
	v_fmac_f32_e32 v16, v0, v0
	v_fmac_f32_e32 v16, v1, v1
	v_fmac_f32_e32 v16, v2, v2
	v_pk_mul_f32 v[4:5], v[4:5], v[36:37] op_sel_hi:[1,0]
	v_fmac_f32_e32 v16, v3, v3
	v_fmac_f32_e32 v16, v4, v4
	v_pk_mul_f32 v[6:7], v[6:7], v[36:37] op_sel_hi:[1,0]
	v_fmac_f32_e32 v16, v5, v5
	v_fmac_f32_e32 v16, v6, v6
	v_pk_mul_f32 v[8:9], v[8:9], v[36:37] op_sel_hi:[1,0]
	v_fmac_f32_e32 v16, v7, v7
	v_fmac_f32_e32 v16, v8, v8
	v_pk_mul_f32 v[10:11], v[10:11], v[36:37] op_sel_hi:[1,0]
	v_fmac_f32_e32 v16, v9, v9
	v_fmac_f32_e32 v16, v10, v10
	v_pk_mul_f32 v[12:13], v[12:13], v[36:37] op_sel_hi:[1,0]
	v_fmac_f32_e32 v16, v11, v11
	v_fmac_f32_e32 v16, v12, v12
	v_pk_mul_f32 v[14:15], v[14:15], v[36:37] op_sel_hi:[1,0]
	v_fmac_f32_e32 v16, v13, v13
	v_fmac_f32_e32 v16, v14, v14
	v_fmac_f32_e32 v16, v15, v15
	v_mov_b32_e32 v17, v16
	s_nop 1
	v_permlane32_swap_b32_e32 v17, v16
	v_cmp_gt_u32_e32 vcc, 32, v232
	s_and_saveexec_b64 s[0:1], vcc
	s_cbranch_execz .LBB0_284
	s_lshl_b32 s4, s10, 2
	v_lshlrev_b32_e32 v18, 2, v164
	s_add_i32 s4, s4, s20
	v_lshlrev_b32_e32 v19, 2, v252
	v_add3_u32 v18, s4, v18, v19
	v_add_f32_e32 v16, v16, v17
	ds_write_b32 v18, v16
	.LBB0_284:
	s_or_b64 exec, exec, s[0:1]
	s_waitcnt lgkmcnt(0)
	s_barrier
	v_mov_b32_e32 v225, 0x358637bd
	v_mov_b32_e32 v226, 0x260
	v_lshlrev_b32_e32 v112, 2, v199
	s_lshl_b32 s4, s10, 2
	s_add_i32 s4, s20, s4
	v_lshl_add_u32 v18, v252, 2, s4
	ds_read2st64_b32 v[16:17], v18 offset1:1
	ds_read2st64_b32 v[36:37], v18 offset0:2 offset1:3
	ds_read2st64_b32 v[38:39], v18 offset0:4 offset1:5
	ds_read2st64_b32 v[40:41], v18 offset0:6 offset1:7
	v_mov_b32_e32 v224, v248
	v_add_u32_e32 v227, -1, v236
	v_add_u32_e32 v228, -2, v236
	v_add_u32_e32 v229, -4, v236
	v_add_u32_e32 v230, -8, v236
	v_add_u32_e32 v231, -16, v236
	v_subrev_u32_e32 v232, 32, v236
	v_bfrev_b32_e32 v233, 0.5
	v_mov_b32_e32 v234, 0x1400
	v_mov_b32_e32 v235, 0x1000
	v_mov_b32_e32 v239, 0xf800000
	v_mov_b32_e32 v240, 0xf400000
	s_waitcnt lgkmcnt(0)
	v_add_f32_e32 v16, 0, v16
	v_add_f32_e32 v19, v16, v17
	v_add_f32_e32 v16, v19, v36
	v_add_f32_e32 v19, v16, v37
	v_add_f32_e32 v16, v19, v38
	v_add_f32_e32 v19, v16, v39
	v_add_f32_e32 v16, v19, v40
	v_add_f32_e32 v16, v16, v41
	v_fmamk_f32 v16, v16, 0x3b000000, v225
	s_mov_b32 s0, 0xf800000
	v_cmp_gt_f32_e32 vcc, s0, v16
	v_mul_f32_e32 v17, 0x4f800000, v16
	v_cndmask_b32_e32 v16, v16, v17, vcc
	v_sqrt_f32_e32 v17, v16
	v_lshlrev_b32_e32 v112, 1, v199
	v_add_u32_e32 v36, -1, v17
	v_fma_f32 v37, -v36, v17, v16
	v_cmp_ge_f32_e64 s[38:39], 0, v37
	v_add_u32_e32 v37, 1, v17
	s_nop 0
	v_cndmask_b32_e64 v36, v17, v36, s[38:39]
	v_fma_f32 v17, -v37, v17, v16
	v_cmp_lt_f32_e64 s[38:39], 0, v17
	s_nop 1
	v_cndmask_b32_e64 v17, v36, v37, s[38:39]
	v_mul_f32_e32 v36, 0x37800000, v17
	v_cndmask_b32_e32 v17, v17, v36, vcc
	v_cmp_class_f32_e32 vcc, v16, v226
	s_nop 1
	v_cndmask_b32_e32 v16, v17, v16, vcc
	v_div_scale_f32 v17, s[0:1], v16, v16, 1.0
	v_rcp_f32_e32 v36, v17
	s_mov_b64 s[0:1], 0x1e00000
	v_fma_f32 v37, -v17, v36, 1.0
	v_fmac_f32_e32 v36, v37, v36
	v_div_scale_f32 v37, vcc, 1.0, v16, 1.0
	v_mul_f32_e32 v38, v37, v36
	v_fma_f32 v39, -v17, v38, v37
	v_fmac_f32_e32 v38, v39, v36
	v_fma_f32 v17, -v17, v38, v37
	v_div_fmas_f32 v17, v17, v36, v38
	v_lshlrev_b64 v[36:37], 11, v[162:163]
	v_div_fixup_f32 v16, v17, v16, 1.0
	v_lshl_add_u64 v[36:37], s[2:3], 0, v[36:37]
	v_lshl_add_u64 v[36:37], v[164:165], 1, v[36:37]
	v_pk_mul_f32 v[34:35], v[34:35], v[16:17] op_sel_hi:[1,0]
	v_pk_mul_f32 v[32:33], v[32:33], v[16:17] op_sel_hi:[1,0]
	v_lshl_add_u64 v[36:37], v[36:37], 0, v[112:113]
	v_pk_mul_f32 v[20:21], v[20:21], v[16:17] op_sel_hi:[1,0]
	v_pk_mul_f32 v[22:23], v[22:23], v[16:17] op_sel_hi:[1,0]
	v_pk_mul_f32 v[24:25], v[24:25], v[16:17] op_sel_hi:[1,0]
	v_pk_mul_f32 v[0:1], v[0:1], v[16:17] op_sel_hi:[1,0]
	v_pk_mul_f32 v[2:3], v[2:3], v[16:17] op_sel_hi:[1,0]
	v_pk_mul_f32 v[4:5], v[4:5], v[16:17] op_sel_hi:[1,0]
	s_waitcnt vmcnt(7)
	v_pk_mul_f32 v[34:35], v[126:127], v[34:35]
	v_pk_mul_f32 v[32:33], v[128:129], v[32:33]
	v_cvt_pk_bf16_f32 v34, v34, v35
	v_cvt_pk_bf16_f32 v35, v32, v33
	v_lshl_add_u64 v[32:33], v[36:37], 0, s[0:1]
	s_mov_b32 s0, 0x1e00000
	v_add_co_u32_e32 v36, vcc, s0, v36
	s_mov_b64 s[0:1], 0
	s_nop 0
	v_addc_co_u32_e32 v37, vcc, 0, v37, vcc
	global_store_dwordx2 v[36:37], v[34:35], off
	s_waitcnt vmcnt(7)
	v_pk_mul_f32 v[20:21], v[96:97], v[20:21]
	v_pk_mul_f32 v[22:23], v[98:99], v[22:23]
	v_cvt_pk_bf16_f32 v20, v20, v21
	v_cvt_pk_bf16_f32 v21, v22, v23
	global_store_dwordx2 v[32:33], v[20:21], off offset:16
	s_waitcnt vmcnt(7)
	v_pk_mul_f32 v[20:21], v[24:25], v[100:101]
	v_pk_mul_f32 v[24:25], v[26:27], v[16:17] op_sel_hi:[1,0]
	v_cvt_pk_bf16_f32 v20, v20, v21
	v_pk_mul_f32 v[22:23], v[24:25], v[102:103]
	v_pk_mul_f32 v[24:25], v[28:29], v[16:17] op_sel_hi:[1,0]
	v_cvt_pk_bf16_f32 v21, v22, v23
	global_store_dwordx2 v[32:33], v[20:21], off offset:32
	s_waitcnt vmcnt(7)
	v_pk_mul_f32 v[20:21], v[24:25], v[104:105]
	v_pk_mul_f32 v[24:25], v[30:31], v[16:17] op_sel_hi:[1,0]
	v_cvt_pk_bf16_f32 v20, v20, v21
	v_pk_mul_f32 v[22:23], v[24:25], v[106:107]
	s_nop 0
	v_cvt_pk_bf16_f32 v21, v22, v23
	global_store_dwordx2 v[32:33], v[20:21], off offset:48
	s_waitcnt vmcnt(7)
	v_pk_mul_f32 v[0:1], v[0:1], v[108:109]
	v_pk_mul_f32 v[2:3], v[2:3], v[110:111]
	v_cvt_pk_bf16_f32 v0, v0, v1
	v_cvt_pk_bf16_f32 v1, v2, v3
	global_store_dwordx2 v[32:33], v[0:1], off offset:64
	s_waitcnt vmcnt(7)
	v_pk_mul_f32 v[0:1], v[4:5], v[114:115]
	v_pk_mul_f32 v[4:5], v[6:7], v[16:17] op_sel_hi:[1,0]
	v_cvt_pk_bf16_f32 v0, v0, v1
	v_pk_mul_f32 v[2:3], v[4:5], v[116:117]
	v_pk_mul_f32 v[4:5], v[8:9], v[16:17] op_sel_hi:[1,0]
	v_cvt_pk_bf16_f32 v1, v2, v3
	global_store_dwordx2 v[32:33], v[0:1], off offset:80
	s_waitcnt vmcnt(7)
	v_pk_mul_f32 v[0:1], v[4:5], v[118:119]
	v_pk_mul_f32 v[4:5], v[10:11], v[16:17] op_sel_hi:[1,0]
	v_cvt_pk_bf16_f32 v0, v0, v1
	v_pk_mul_f32 v[2:3], v[4:5], v[120:121]
	v_pk_mul_f32 v[4:5], v[12:13], v[16:17] op_sel_hi:[1,0]
	v_cvt_pk_bf16_f32 v1, v2, v3
	global_store_dwordx2 v[32:33], v[0:1], off offset:96
	s_waitcnt vmcnt(7)
	v_pk_mul_f32 v[0:1], v[4:5], v[122:123]
	v_pk_mul_f32 v[4:5], v[14:15], v[16:17] op_sel_hi:[1,0]
	v_cvt_pk_bf16_f32 v0, v0, v1
	v_pk_mul_f32 v[2:3], v[4:5], v[124:125]
	s_nop 0
	v_cvt_pk_bf16_f32 v1, v2, v3
	global_store_dwordx2 v[32:33], v[0:1], off offset:112
	s_barrier
